# v093 + RG-LRU gate section: waves 4-7 run their partner tile before the first tile, so the two waves of each SIMD are out of phase (one in MFMA while the other is in the VALU epilogue)
# speedup vs baseline: 1.0005x; 1.0005x over previous
; #define LAS __attribute__((address_space(3)))
; DI void phase_rglru(const Params& p, unsigned char* shm) {
;     ...
;             {
; #pragma unroll
;                 for (int u = 0; u < 2; ++u) {
;                     if (u == 1 && w >= 4) break;
;                     f32x4 acc[4][2];
; #pragma unroll
;                     for (int mt = 0; mt < 4; ++mt) { acc[mt][0] = (f32x4){0.f, 0.f, 0.f, 0.f}; acc[mt][1] = (f32x4){0.f, 0.f, 0.f, 0.f}; }
; #pragma unroll
;                     for (int kk = 0; kk < 6; ++kk)
; #pragma unroll
;                         for (int mt = 0; mt < 4; ++mt) {
;                             const bf16x8 af = *(const LAS bf16x8*)(lds + XC + (16 * mt + fr) * TR + (32 * kk + 8 * fq) * 2);
;                             acc[mt][0] = __builtin_amdgcn_mfma_f32_16x16x32_bf16(af, Bf[u][kk], acc[mt][0], 0, 0, 0);
;                             acc[mt][1] = __builtin_amdgcn_mfma_f32_16x16x32_bf16(af, Bf[2 + u][kk], acc[mt][1], 0, 0, 0);
;                         }
;                     const int ch = chb + 16 * u + fr;
;                     const float ba = gb[ch], bx = gb[192 + ch], sp = gb[384 + ch];
.Lconv_x_done:
	s_or_b64 exec, exec, s[2:3]
	s_waitcnt lgkmcnt(0)
	s_barrier
	s_andn2_b64 vcc, exec, s[12:13]
	s_cbranch_vccnz .Lgates_b
	ds_read_b128 v[120:123], v204 offset:26880
	ds_read_b128 v[124:127], v204 offset:33280
	ds_read_b128 v[128:131], v204 offset:39680
	ds_read_b128 v[132:135], v204 offset:46080
	ds_read_b128 v[226:229], v204 offset:26944
	s_waitcnt lgkmcnt(4)
	v_mfma_f32_16x16x32_bf16 v[148:151], v[120:123], v[0:3], 0
	v_mfma_f32_16x16x32_bf16 v[144:147], v[120:123], v[48:51], 0
	ds_read_b128 v[230:233], v204 offset:33344
	s_waitcnt lgkmcnt(4)
	v_mfma_f32_16x16x32_bf16 v[140:143], v[124:127], v[0:3], 0
	v_mfma_f32_16x16x32_bf16 v[136:139], v[124:127], v[48:51], 0
	ds_read_b128 v[120:123], v204 offset:39744
	s_waitcnt lgkmcnt(4)
	v_mfma_f32_16x16x32_bf16 v[214:217], v[128:131], v[0:3], 0
	v_mfma_f32_16x16x32_bf16 v[210:213], v[128:131], v[48:51], 0
	ds_read_b128 v[124:127], v204 offset:46144
	s_waitcnt lgkmcnt(4)
	v_mfma_f32_16x16x32_bf16 v[218:221], v[132:135], v[0:3], 0
	v_mfma_f32_16x16x32_bf16 v[222:225], v[132:135], v[48:51], 0
	ds_read_b128 v[128:131], v204 offset:27008
	s_waitcnt lgkmcnt(4)
	v_mfma_f32_16x16x32_bf16 v[148:151], v[226:229], v[4:7], v[148:151]
	v_mfma_f32_16x16x32_bf16 v[144:147], v[226:229], v[52:55], v[144:147]
	ds_read_b128 v[132:135], v204 offset:33408
	s_waitcnt lgkmcnt(4)
	v_mfma_f32_16x16x32_bf16 v[140:143], v[230:233], v[4:7], v[140:143]
	v_mfma_f32_16x16x32_bf16 v[136:139], v[230:233], v[52:55], v[136:139]
	ds_read_b128 v[226:229], v204 offset:39808
	s_waitcnt lgkmcnt(4)
	v_mfma_f32_16x16x32_bf16 v[214:217], v[120:123], v[4:7], v[214:217]
	v_mfma_f32_16x16x32_bf16 v[210:213], v[120:123], v[52:55], v[210:213]
	ds_read_b128 v[230:233], v204 offset:46208
	s_waitcnt lgkmcnt(4)
	v_mfma_f32_16x16x32_bf16 v[218:221], v[124:127], v[4:7], v[218:221]
	v_mfma_f32_16x16x32_bf16 v[222:225], v[124:127], v[52:55], v[222:225]
	ds_read_b128 v[120:123], v204 offset:27072
	s_waitcnt lgkmcnt(4)
	v_mfma_f32_16x16x32_bf16 v[148:151], v[128:131], v[8:11], v[148:151]
	v_mfma_f32_16x16x32_bf16 v[144:147], v[128:131], v[56:59], v[144:147]
	ds_read_b128 v[124:127], v204 offset:33472
	s_waitcnt lgkmcnt(4)
	v_mfma_f32_16x16x32_bf16 v[140:143], v[132:135], v[8:11], v[140:143]
	v_mfma_f32_16x16x32_bf16 v[136:139], v[132:135], v[56:59], v[136:139]
	ds_read_b128 v[128:131], v204 offset:39872
	s_waitcnt lgkmcnt(4)
	v_mfma_f32_16x16x32_bf16 v[214:217], v[226:229], v[8:11], v[214:217]
	v_mfma_f32_16x16x32_bf16 v[210:213], v[226:229], v[56:59], v[210:213]
	ds_read_b128 v[132:135], v204 offset:46272
	s_waitcnt lgkmcnt(4)
	v_mfma_f32_16x16x32_bf16 v[218:221], v[230:233], v[8:11], v[218:221]
	v_mfma_f32_16x16x32_bf16 v[222:225], v[230:233], v[56:59], v[222:225]
	ds_read_b128 v[226:229], v204 offset:27136
	s_waitcnt lgkmcnt(4)
	v_mfma_f32_16x16x32_bf16 v[148:151], v[120:123], v[12:15], v[148:151]
	v_mfma_f32_16x16x32_bf16 v[144:147], v[120:123], v[60:63], v[144:147]
	ds_read_b128 v[230:233], v204 offset:33536
	s_waitcnt lgkmcnt(4)
	v_mfma_f32_16x16x32_bf16 v[140:143], v[124:127], v[12:15], v[140:143]
	v_mfma_f32_16x16x32_bf16 v[136:139], v[124:127], v[60:63], v[136:139]
	ds_read_b128 v[120:123], v204 offset:39936
	s_waitcnt lgkmcnt(4)
	v_mfma_f32_16x16x32_bf16 v[214:217], v[128:131], v[12:15], v[214:217]
	v_mfma_f32_16x16x32_bf16 v[210:213], v[128:131], v[60:63], v[210:213]
	ds_read_b128 v[124:127], v204 offset:46336
	s_waitcnt lgkmcnt(4)
	v_mfma_f32_16x16x32_bf16 v[218:221], v[132:135], v[12:15], v[218:221]
	v_mfma_f32_16x16x32_bf16 v[222:225], v[132:135], v[60:63], v[222:225]
	ds_read_b128 v[128:131], v204 offset:27200
	s_waitcnt lgkmcnt(4)
	v_mfma_f32_16x16x32_bf16 v[148:151], v[226:229], v[16:19], v[148:151]
	v_mfma_f32_16x16x32_bf16 v[144:147], v[226:229], v[64:67], v[144:147]
	ds_read_b128 v[132:135], v204 offset:33600
	s_waitcnt lgkmcnt(4)
	v_mfma_f32_16x16x32_bf16 v[140:143], v[230:233], v[16:19], v[140:143]
	v_mfma_f32_16x16x32_bf16 v[136:139], v[230:233], v[64:67], v[136:139]
	s_waitcnt lgkmcnt(3)
	v_mfma_f32_16x16x32_bf16 v[214:217], v[120:123], v[16:19], v[214:217]
	v_mfma_f32_16x16x32_bf16 v[210:213], v[120:123], v[64:67], v[210:213]
	s_waitcnt lgkmcnt(2)
	v_mfma_f32_16x16x32_bf16 v[218:221], v[124:127], v[16:19], v[218:221]
	v_mfma_f32_16x16x32_bf16 v[222:225], v[124:127], v[64:67], v[222:225]
	s_waitcnt lgkmcnt(1)
	v_mfma_f32_16x16x32_bf16 v[148:151], v[128:131], v[20:23], v[148:151]
	v_mfma_f32_16x16x32_bf16 v[144:147], v[128:131], v[68:71], v[144:147]
	s_waitcnt lgkmcnt(0)
	v_mfma_f32_16x16x32_bf16 v[140:143], v[132:135], v[20:23], v[140:143]
	v_mfma_f32_16x16x32_bf16 v[136:139], v[132:135], v[68:71], v[136:139]
	ds_read_b128 v[120:123], v204 offset:40000
	s_nop 1
	ds_read_b128 v[128:131], v204 offset:46400
	ds_read2st64_b32 v[170:171], v184 offset1:3
	ds_read_b32 v205, v184 offset:1536
	ds_read_u16 v226, v194 offset:26880
	ds_read_u16 v227, v194 offset:27280
	ds_read_u16 v228, v194 offset:27680
	ds_read_u16 v229, v194 offset:28080
	ds_read_u16 v230, v194 offset:33280
	ds_read_u16 v231, v194 offset:33680
	ds_read_u16 v232, v194 offset:34080
	ds_read_u16 v233, v194 offset:34480
	ds_read_u16 v234, v194 offset:39680
	ds_read_u16 v235, v194 offset:40080
	ds_read_u16 v236, v194 offset:40480
	ds_read_u16 v237, v194 offset:40880
	ds_read_u16 v238, v194 offset:46080
	ds_read_u16 v239, v194 offset:46480
	ds_read_u16 v240, v194 offset:46880
	ds_read_u16 v241, v194 offset:47280
	s_waitcnt lgkmcnt(15)
; DI void phase_rglru(const Params& p, unsigned char* shm) {
;     ...
;                     const float ba = gb[ch], bx = gb[192 + ch], sp = gb[384 + ch];
; #pragma unroll
;                     for (int mt = 0; mt < 4; ++mt)
; #pragma unroll
;                         for (int j = 0; j < 4; ++j) {
;                             const int t = 16 * mt + 4 * fq + j;
;                             const float ea = 1.f + __expf(fminf(-(acc[mt][0][j] + ba), 40.f)), ex = 1.f + __expf(fminf(-(acc[mt][1][j] + bx), 40.f));
;                             const float inv = __builtin_amdgcn_rcpf(ea * ex);
;                             const float r = inv * ex, ig = inv * ea;
	v_mov_b32_e32 v242, 0xbfb8aa3b
	v_mov_b32_e32 v243, 0x4266d4ca
	v_mul_f32_e32 v170, v242, v170
	v_mul_f32_e32 v171, v242, v171
	v_mul_f32_e32 v205, 0x3fb8aa3b, v205
	v_mfma_f32_16x16x32_bf16 v[124:127], v[120:123], v[20:23], v[214:217]
	v_mfma_f32_16x16x32_bf16 v[120:123], v[120:123], v[68:71], v[210:213]
	v_mfma_f32_16x16x32_bf16 v[132:135], v[128:131], v[20:23], v[218:221]
	v_mfma_f32_16x16x32_bf16 v[128:131], v[128:131], v[68:71], v[222:225]
	v_pk_fma_f32 v[148:149], v[148:149], v[242:243], v[170:171] op_sel_hi:[1,0,0]
	v_pk_fma_f32 v[144:145], v[144:145], v[242:243], v[170:171] op_sel:[0,0,1] op_sel_hi:[1,0,1]
	v_pk_fma_f32 v[150:151], v[150:151], v[242:243], v[170:171] op_sel_hi:[1,0,0]
	v_pk_fma_f32 v[146:147], v[146:147], v[242:243], v[170:171] op_sel:[0,0,1] op_sel_hi:[1,0,1]
	v_pk_fma_f32 v[140:141], v[140:141], v[242:243], v[170:171] op_sel_hi:[1,0,0]
	v_pk_fma_f32 v[136:137], v[136:137], v[242:243], v[170:171] op_sel:[0,0,1] op_sel_hi:[1,0,1]
	v_pk_fma_f32 v[142:143], v[142:143], v[242:243], v[170:171] op_sel_hi:[1,0,0]
	v_pk_fma_f32 v[138:139], v[138:139], v[242:243], v[170:171] op_sel:[0,0,1] op_sel_hi:[1,0,1]
	s_nop 0
	v_pk_fma_f32 v[124:125], v[124:125], v[242:243], v[170:171] op_sel_hi:[1,0,0]
	v_pk_fma_f32 v[120:121], v[120:121], v[242:243], v[170:171] op_sel:[0,0,1] op_sel_hi:[1,0,1]
	v_pk_fma_f32 v[126:127], v[126:127], v[242:243], v[170:171] op_sel_hi:[1,0,0]
	v_pk_fma_f32 v[122:123], v[122:123], v[242:243], v[170:171] op_sel:[0,0,1] op_sel_hi:[1,0,1]
	v_pk_fma_f32 v[132:133], v[132:133], v[242:243], v[170:171] op_sel_hi:[1,0,0]
	v_pk_fma_f32 v[128:129], v[128:129], v[242:243], v[170:171] op_sel:[0,0,1] op_sel_hi:[1,0,1]
	v_pk_fma_f32 v[134:135], v[134:135], v[242:243], v[170:171] op_sel_hi:[1,0,0]
	v_pk_fma_f32 v[130:131], v[130:131], v[242:243], v[170:171] op_sel:[0,0,1] op_sel_hi:[1,0,1]
	v_min_f32_e32 v148, v243, v148
	v_min_f32_e32 v149, v243, v149
	v_min_f32_e32 v144, v243, v144
	v_min_f32_e32 v145, v243, v145
	v_min_f32_e32 v150, v243, v150
	v_min_f32_e32 v151, v243, v151
	v_min_f32_e32 v146, v243, v146
	v_min_f32_e32 v147, v243, v147
	v_min_f32_e32 v140, v243, v140
	v_min_f32_e32 v141, v243, v141
	v_min_f32_e32 v136, v243, v136
	v_min_f32_e32 v137, v243, v137
	v_min_f32_e32 v142, v243, v142
	v_min_f32_e32 v143, v243, v143
	v_min_f32_e32 v138, v243, v138
	v_min_f32_e32 v139, v243, v139
	v_min_f32_e32 v124, v243, v124
	v_min_f32_e32 v125, v243, v125
	v_min_f32_e32 v120, v243, v120
	v_min_f32_e32 v121, v243, v121
	v_min_f32_e32 v126, v243, v126
	v_min_f32_e32 v127, v243, v127
	v_min_f32_e32 v122, v243, v122
	v_min_f32_e32 v123, v243, v123
	v_min_f32_e32 v132, v243, v132
	v_min_f32_e32 v133, v243, v133
	v_min_f32_e32 v128, v243, v128
	v_min_f32_e32 v129, v243, v129
	v_min_f32_e32 v134, v243, v134
	v_min_f32_e32 v135, v243, v135
	v_min_f32_e32 v130, v243, v130
	v_min_f32_e32 v131, v243, v131
	v_exp_f32_e32 v148, v148
	v_exp_f32_e32 v149, v149
	v_exp_f32_e32 v144, v144
	v_exp_f32_e32 v145, v145
	v_exp_f32_e32 v150, v150
	v_exp_f32_e32 v151, v151
	v_exp_f32_e32 v146, v146
	v_exp_f32_e32 v147, v147
	v_exp_f32_e32 v140, v140
	v_exp_f32_e32 v141, v141
	v_exp_f32_e32 v136, v136
	v_exp_f32_e32 v137, v137
	v_exp_f32_e32 v142, v142
	v_exp_f32_e32 v143, v143
	v_exp_f32_e32 v138, v138
	v_exp_f32_e32 v139, v139
	v_exp_f32_e32 v124, v124
	v_exp_f32_e32 v125, v125
	v_exp_f32_e32 v120, v120
	v_exp_f32_e32 v121, v121
	v_exp_f32_e32 v126, v126
	v_exp_f32_e32 v127, v127
	v_exp_f32_e32 v122, v122
	v_exp_f32_e32 v123, v123
	v_exp_f32_e32 v132, v132
	v_exp_f32_e32 v133, v133
	v_exp_f32_e32 v128, v128
	v_exp_f32_e32 v129, v129
	v_exp_f32_e32 v134, v134
	v_exp_f32_e32 v135, v135
	v_exp_f32_e32 v130, v130
	v_exp_f32_e32 v131, v131
	v_pk_add_f32 v[148:149], v[148:149], 1.0 op_sel_hi:[1,0]
	v_pk_add_f32 v[144:145], v[144:145], 1.0 op_sel_hi:[1,0]
	v_pk_add_f32 v[150:151], v[150:151], 1.0 op_sel_hi:[1,0]
	v_pk_add_f32 v[146:147], v[146:147], 1.0 op_sel_hi:[1,0]
	v_pk_add_f32 v[140:141], v[140:141], 1.0 op_sel_hi:[1,0]
	v_pk_add_f32 v[136:137], v[136:137], 1.0 op_sel_hi:[1,0]
	v_pk_add_f32 v[142:143], v[142:143], 1.0 op_sel_hi:[1,0]
	v_pk_add_f32 v[138:139], v[138:139], 1.0 op_sel_hi:[1,0]
	v_pk_add_f32 v[124:125], v[124:125], 1.0 op_sel_hi:[1,0]
	v_pk_add_f32 v[120:121], v[120:121], 1.0 op_sel_hi:[1,0]
	v_pk_add_f32 v[126:127], v[126:127], 1.0 op_sel_hi:[1,0]
	v_pk_add_f32 v[122:123], v[122:123], 1.0 op_sel_hi:[1,0]
	v_pk_add_f32 v[132:133], v[132:133], 1.0 op_sel_hi:[1,0]
	v_pk_add_f32 v[128:129], v[128:129], 1.0 op_sel_hi:[1,0]
	v_pk_add_f32 v[134:135], v[134:135], 1.0 op_sel_hi:[1,0]
	v_pk_add_f32 v[130:131], v[130:131], 1.0 op_sel_hi:[1,0]
	v_pk_mul_f32 v[210:211], v[148:149], v[144:145]
	v_pk_mul_f32 v[212:213], v[150:151], v[146:147]
	v_pk_mul_f32 v[214:215], v[140:141], v[136:137]
	v_pk_mul_f32 v[216:217], v[142:143], v[138:139]
	v_pk_mul_f32 v[218:219], v[124:125], v[120:121]
	v_pk_mul_f32 v[220:221], v[126:127], v[122:123]
	v_pk_mul_f32 v[222:223], v[132:133], v[128:129]
	v_pk_mul_f32 v[224:225], v[134:135], v[130:131]
	v_rcp_f32_e32 v210, v210
	v_rcp_f32_e32 v211, v211
	v_rcp_f32_e32 v212, v212
	v_rcp_f32_e32 v213, v213
	v_rcp_f32_e32 v214, v214
	v_rcp_f32_e32 v215, v215
	v_rcp_f32_e32 v216, v216
	v_rcp_f32_e32 v217, v217
	v_rcp_f32_e32 v218, v218
	v_rcp_f32_e32 v219, v219
	v_rcp_f32_e32 v220, v220
	v_rcp_f32_e32 v221, v221
	v_rcp_f32_e32 v222, v222
	v_rcp_f32_e32 v223, v223
	v_rcp_f32_e32 v224, v224
	v_rcp_f32_e32 v225, v225
	v_pk_mul_f32 v[144:145], v[144:145], v[210:211]
	v_pk_mul_f32 v[148:149], v[148:149], v[210:211]
	v_pk_mul_f32 v[146:147], v[146:147], v[212:213]
	v_pk_mul_f32 v[150:151], v[150:151], v[212:213]
; #define LAS __attribute__((address_space(3)))
; DI unsigned pk2(float a, float b) { f32x2 v = {a, b}; bf2_t r = __builtin_convertvector(v, bf2_t); return __builtin_bit_cast(unsigned, r); }
; DI void phase_rglru(const Params& p, unsigned char* shm) {
;     ...
;                             const float ea = 1.f + __expf(fminf(-(acc[mt][0][j] + ba), 40.f)), ex = 1.f + __expf(fminf(-(acc[mt][1][j] + bx), 40.f));
;                             const float inv = __builtin_amdgcn_rcpf(ea * ex);
;                             const float r = inv * ex, ig = inv * ea;
;                             const float av = __expf(r * sp), om = 1.f - av;
;                             const float xcv = __uint_as_float((unsigned)*(const LAS bf16_t*)(lds + XC + t * TR + ch * 2) << 16);
;                             const float bt = __builtin_amdgcn_sqrtf(fmaxf(om * (1.f + av), 0.f)) * (ig * xcv);
;                             *(LAS bf16_t*)(lds + LAo + t * TR + ch * 2) = (bf16_t)(pk2(om, 0.f) & 0xffffu);
;                             *(LAS bf16_t*)(lds + BTo + t * TR + ch * 2) = (bf16_t)(pk2(bt, 0.f) & 0xffffu);
	v_pk_mul_f32 v[136:137], v[136:137], v[214:215]
	v_pk_mul_f32 v[140:141], v[140:141], v[214:215]
	v_pk_mul_f32 v[138:139], v[138:139], v[216:217]
	v_pk_mul_f32 v[142:143], v[142:143], v[216:217]
	v_pk_mul_f32 v[120:121], v[120:121], v[218:219]
	v_pk_mul_f32 v[124:125], v[124:125], v[218:219]
	v_pk_mul_f32 v[122:123], v[122:123], v[220:221]
	v_pk_mul_f32 v[126:127], v[126:127], v[220:221]
	v_pk_mul_f32 v[128:129], v[128:129], v[222:223]
	v_pk_mul_f32 v[132:133], v[132:133], v[222:223]
	v_pk_mul_f32 v[130:131], v[130:131], v[224:225]
	v_pk_mul_f32 v[134:135], v[134:135], v[224:225]
	v_pk_mul_f32 v[144:145], v[144:145], v[204:205] op_sel:[0,1] op_sel_hi:[1,1]
	v_pk_mul_f32 v[146:147], v[146:147], v[204:205] op_sel:[0,1] op_sel_hi:[1,1]
	v_pk_mul_f32 v[136:137], v[136:137], v[204:205] op_sel:[0,1] op_sel_hi:[1,1]
	v_pk_mul_f32 v[138:139], v[138:139], v[204:205] op_sel:[0,1] op_sel_hi:[1,1]
	v_pk_mul_f32 v[120:121], v[120:121], v[204:205] op_sel:[0,1] op_sel_hi:[1,1]
	v_pk_mul_f32 v[122:123], v[122:123], v[204:205] op_sel:[0,1] op_sel_hi:[1,1]
	v_pk_mul_f32 v[128:129], v[128:129], v[204:205] op_sel:[0,1] op_sel_hi:[1,1]
	v_pk_mul_f32 v[130:131], v[130:131], v[204:205] op_sel:[0,1] op_sel_hi:[1,1]
	v_exp_f32_e32 v144, v144
	v_exp_f32_e32 v145, v145
	v_exp_f32_e32 v146, v146
	v_exp_f32_e32 v147, v147
	v_exp_f32_e32 v136, v136
	v_exp_f32_e32 v137, v137
	v_exp_f32_e32 v138, v138
	v_exp_f32_e32 v139, v139
	v_exp_f32_e32 v120, v120
	v_exp_f32_e32 v121, v121
	v_exp_f32_e32 v122, v122
	v_exp_f32_e32 v123, v123
	v_exp_f32_e32 v128, v128
	v_exp_f32_e32 v129, v129
	v_exp_f32_e32 v130, v130
	v_exp_f32_e32 v131, v131
	v_pk_add_f32 v[210:211], v[144:145], 1.0 op_sel_hi:[1,0] neg_lo:[1,0] neg_hi:[1,0]
	v_pk_add_f32 v[144:145], v[144:145], 1.0 op_sel_hi:[1,0]
	v_pk_add_f32 v[212:213], v[146:147], 1.0 op_sel_hi:[1,0] neg_lo:[1,0] neg_hi:[1,0]
	v_pk_add_f32 v[146:147], v[146:147], 1.0 op_sel_hi:[1,0]
	v_pk_add_f32 v[214:215], v[136:137], 1.0 op_sel_hi:[1,0] neg_lo:[1,0] neg_hi:[1,0]
	v_pk_add_f32 v[136:137], v[136:137], 1.0 op_sel_hi:[1,0]
	v_pk_add_f32 v[216:217], v[138:139], 1.0 op_sel_hi:[1,0] neg_lo:[1,0] neg_hi:[1,0]
	v_pk_add_f32 v[138:139], v[138:139], 1.0 op_sel_hi:[1,0]
	v_pk_add_f32 v[218:219], v[120:121], 1.0 op_sel_hi:[1,0] neg_lo:[1,0] neg_hi:[1,0]
	v_pk_add_f32 v[120:121], v[120:121], 1.0 op_sel_hi:[1,0]
	v_pk_add_f32 v[220:221], v[122:123], 1.0 op_sel_hi:[1,0] neg_lo:[1,0] neg_hi:[1,0]
	v_pk_add_f32 v[122:123], v[122:123], 1.0 op_sel_hi:[1,0]
	v_pk_add_f32 v[222:223], v[128:129], 1.0 op_sel_hi:[1,0] neg_lo:[1,0] neg_hi:[1,0]
	v_pk_add_f32 v[128:129], v[128:129], 1.0 op_sel_hi:[1,0]
	v_pk_add_f32 v[224:225], v[130:131], 1.0 op_sel_hi:[1,0] neg_lo:[1,0] neg_hi:[1,0]
	v_pk_add_f32 v[130:131], v[130:131], 1.0 op_sel_hi:[1,0]
	v_pk_mul_f32 v[144:145], v[210:211], v[144:145]
	v_pk_mul_f32 v[146:147], v[212:213], v[146:147]
	v_pk_mul_f32 v[136:137], v[214:215], v[136:137]
	v_pk_mul_f32 v[138:139], v[216:217], v[138:139]
	v_pk_mul_f32 v[120:121], v[218:219], v[120:121]
	v_pk_mul_f32 v[122:123], v[220:221], v[122:123]
	v_pk_mul_f32 v[128:129], v[222:223], v[128:129]
	v_pk_mul_f32 v[130:131], v[224:225], v[130:131]
	v_max_f32_e32 v144, 0, v144
	v_max_f32_e32 v145, 0, v145
	v_max_f32_e32 v146, 0, v146
	v_max_f32_e32 v147, 0, v147
	v_max_f32_e32 v136, 0, v136
	v_max_f32_e32 v137, 0, v137
	v_max_f32_e32 v138, 0, v138
	v_max_f32_e32 v139, 0, v139
	v_max_f32_e32 v120, 0, v120
	v_max_f32_e32 v121, 0, v121
	v_max_f32_e32 v122, 0, v122
	v_max_f32_e32 v123, 0, v123
	v_max_f32_e32 v128, 0, v128
	v_max_f32_e32 v129, 0, v129
	v_max_f32_e32 v130, 0, v130
	v_max_f32_e32 v131, 0, v131
	v_sqrt_f32_e32 v144, v144
	v_sqrt_f32_e32 v145, v145
	v_sqrt_f32_e32 v146, v146
	v_sqrt_f32_e32 v147, v147
	v_sqrt_f32_e32 v136, v136
	v_sqrt_f32_e32 v137, v137
	v_sqrt_f32_e32 v138, v138
	v_sqrt_f32_e32 v139, v139
	v_sqrt_f32_e32 v120, v120
	v_sqrt_f32_e32 v121, v121
	v_sqrt_f32_e32 v122, v122
	v_sqrt_f32_e32 v123, v123
	v_sqrt_f32_e32 v128, v128
	v_sqrt_f32_e32 v129, v129
	v_sqrt_f32_e32 v130, v130
	v_sqrt_f32_e32 v131, v131
	s_waitcnt lgkmcnt(0)
	v_lshlrev_b32_e32 v226, 16, v226
	v_lshlrev_b32_e32 v227, 16, v227
	v_lshlrev_b32_e32 v228, 16, v228
	v_lshlrev_b32_e32 v229, 16, v229
	v_lshlrev_b32_e32 v230, 16, v230
	v_lshlrev_b32_e32 v231, 16, v231
	v_lshlrev_b32_e32 v232, 16, v232
	v_lshlrev_b32_e32 v233, 16, v233
	v_lshlrev_b32_e32 v234, 16, v234
	v_lshlrev_b32_e32 v235, 16, v235
	v_lshlrev_b32_e32 v236, 16, v236
	v_lshlrev_b32_e32 v237, 16, v237
	v_lshlrev_b32_e32 v238, 16, v238
	v_lshlrev_b32_e32 v239, 16, v239
	v_lshlrev_b32_e32 v240, 16, v240
	v_lshlrev_b32_e32 v241, 16, v241
	v_pk_mul_f32 v[148:149], v[148:149], v[226:227]
	v_pk_mul_f32 v[150:151], v[150:151], v[228:229]
	v_pk_mul_f32 v[140:141], v[140:141], v[230:231]
	v_pk_mul_f32 v[142:143], v[142:143], v[232:233]
	v_pk_mul_f32 v[124:125], v[124:125], v[234:235]
	v_pk_mul_f32 v[126:127], v[126:127], v[236:237]
	v_pk_mul_f32 v[132:133], v[132:133], v[238:239]
	v_pk_mul_f32 v[134:135], v[134:135], v[240:241]
	v_pk_mul_f32 v[148:149], v[148:149], v[144:145]
	v_pk_mul_f32 v[150:151], v[150:151], v[146:147]
	v_pk_mul_f32 v[140:141], v[140:141], v[136:137]
	v_pk_mul_f32 v[142:143], v[142:143], v[138:139]
	v_pk_mul_f32 v[124:125], v[124:125], v[120:121]
	v_pk_mul_f32 v[126:127], v[126:127], v[122:123]
	v_pk_mul_f32 v[132:133], v[132:133], v[128:129]
	v_pk_mul_f32 v[134:135], v[134:135], v[130:131]
	v_cvt_pk_bf16_f32 v210, v210, v211
	v_cvt_pk_bf16_f32 v148, v148, v149
	v_cvt_pk_bf16_f32 v212, v212, v213
	v_cvt_pk_bf16_f32 v150, v150, v151
	v_cvt_pk_bf16_f32 v214, v214, v215
	v_cvt_pk_bf16_f32 v140, v140, v141
	v_cvt_pk_bf16_f32 v216, v216, v217
; #define LAS __attribute__((address_space(3)))
; DI unsigned pk2(float a, float b) { f32x2 v = {a, b}; bf2_t r = __builtin_convertvector(v, bf2_t); return __builtin_bit_cast(unsigned, r); }
; DI void phase_rglru(const Params& p, unsigned char* shm) {
;     ...
;                     for (int kk = 0; kk < 6; ++kk)
; #pragma unroll
;                         for (int mt = 0; mt < 4; ++mt) {
;                             const bf16x8 af = *(const LAS bf16x8*)(lds + XC + (16 * mt + fr) * TR + (32 * kk + 8 * fq) * 2);
;                             acc[mt][0] = __builtin_amdgcn_mfma_f32_16x16x32_bf16(af, Bf[u][kk], acc[mt][0], 0, 0, 0);
;                             acc[mt][1] = __builtin_amdgcn_mfma_f32_16x16x32_bf16(af, Bf[2 + u][kk], acc[mt][1], 0, 0, 0);
;                         }
;                     const int ch = chb + 16 * u + fr;
;                     const float ba = gb[ch], bx = gb[192 + ch], sp = gb[384 + ch];
;     ...
;                             const float av = __expf(r * sp), om = 1.f - av;
;                             const float xcv = __uint_as_float((unsigned)*(const LAS bf16_t*)(lds + XC + t * TR + ch * 2) << 16);
;                             const float bt = __builtin_amdgcn_sqrtf(fmaxf(om * (1.f + av), 0.f)) * (ig * xcv);
;                             *(LAS bf16_t*)(lds + LAo + t * TR + ch * 2) = (bf16_t)(pk2(om, 0.f) & 0xffffu);
;                             *(LAS bf16_t*)(lds + BTo + t * TR + ch * 2) = (bf16_t)(pk2(bt, 0.f) & 0xffffu);
;                         }
	v_cvt_pk_bf16_f32 v142, v142, v143
	v_cvt_pk_bf16_f32 v218, v218, v219
	v_cvt_pk_bf16_f32 v124, v124, v125
	v_cvt_pk_bf16_f32 v220, v220, v221
	v_cvt_pk_bf16_f32 v126, v126, v127
	v_cvt_pk_bf16_f32 v222, v222, v223
	v_cvt_pk_bf16_f32 v132, v132, v133
	v_cvt_pk_bf16_f32 v224, v224, v225
	v_cvt_pk_bf16_f32 v134, v134, v135
	ds_write_b16 v195, v210
	ds_write_b16_d16_hi v195, v210 offset:400
	ds_write_b16 v196, v148
	ds_write_b16_d16_hi v196, v148 offset:400
	ds_write_b16 v195, v212 offset:800
	ds_write_b16_d16_hi v195, v212 offset:1200
	ds_write_b16 v196, v150 offset:800
	ds_write_b16_d16_hi v196, v150 offset:1200
	ds_write_b16 v195, v214 offset:6400
	ds_write_b16_d16_hi v195, v214 offset:6800
	ds_write_b16 v196, v140 offset:6400
	ds_write_b16_d16_hi v196, v140 offset:6800
	ds_write_b16 v195, v216 offset:7200
	ds_write_b16_d16_hi v195, v216 offset:7600
	ds_write_b16 v196, v142 offset:7200
	ds_write_b16_d16_hi v196, v142 offset:7600
	ds_write_b16 v195, v218 offset:12800
	ds_write_b16_d16_hi v195, v218 offset:13200
	ds_write_b16 v196, v124 offset:12800
	ds_write_b16_d16_hi v196, v124 offset:13200
	ds_write_b16 v195, v220 offset:13600
	ds_write_b16_d16_hi v195, v220 offset:14000
	ds_write_b16 v196, v126 offset:13600
	ds_write_b16_d16_hi v196, v126 offset:14000
	ds_write_b16 v195, v222 offset:19200
	ds_write_b16_d16_hi v195, v222 offset:19600
	ds_write_b16 v196, v132 offset:19200
	ds_write_b16_d16_hi v196, v132 offset:19600
	ds_write_b16 v195, v224 offset:20000
	ds_write_b16_d16_hi v195, v224 offset:20400
	ds_write_b16 v196, v134 offset:20000
	ds_write_b16_d16_hi v196, v134 offset:20400
	ds_read_b128 v[120:123], v204 offset:26880
	ds_read_b128 v[124:127], v204 offset:33280
	ds_read_b128 v[128:131], v204 offset:26944
	ds_read_b128 v[132:135], v204 offset:33344
	ds_read_b128 v[226:229], v204 offset:27008
	s_waitcnt lgkmcnt(4)
	v_mfma_f32_16x16x32_bf16 v[148:151], v[120:123], v[24:27], 0
	v_mfma_f32_16x16x32_bf16 v[144:147], v[120:123], v[72:75], 0
	ds_read_b128 v[230:233], v204 offset:33408
	s_waitcnt lgkmcnt(4)
	v_mfma_f32_16x16x32_bf16 v[140:143], v[124:127], v[24:27], 0
	v_mfma_f32_16x16x32_bf16 v[136:139], v[124:127], v[72:75], 0
	ds_read_b128 v[120:123], v204 offset:27072
	s_waitcnt lgkmcnt(4)
	v_mfma_f32_16x16x32_bf16 v[148:151], v[128:131], v[28:31], v[148:151]
	v_mfma_f32_16x16x32_bf16 v[144:147], v[128:131], v[76:79], v[144:147]
	ds_read_b128 v[124:127], v204 offset:33472
	s_waitcnt lgkmcnt(4)
	v_mfma_f32_16x16x32_bf16 v[140:143], v[132:135], v[28:31], v[140:143]
	v_mfma_f32_16x16x32_bf16 v[136:139], v[132:135], v[76:79], v[136:139]
	ds_read_b128 v[128:131], v204 offset:27136
	s_waitcnt lgkmcnt(4)
	v_mfma_f32_16x16x32_bf16 v[148:151], v[226:229], v[32:35], v[148:151]
	v_mfma_f32_16x16x32_bf16 v[144:147], v[226:229], v[80:83], v[144:147]
	ds_read_b128 v[132:135], v204 offset:33536
	s_waitcnt lgkmcnt(4)
	v_mfma_f32_16x16x32_bf16 v[140:143], v[230:233], v[32:35], v[140:143]
	v_mfma_f32_16x16x32_bf16 v[136:139], v[230:233], v[80:83], v[136:139]
	ds_read_b128 v[226:229], v204 offset:27200
	s_waitcnt lgkmcnt(4)
	v_mfma_f32_16x16x32_bf16 v[148:151], v[120:123], v[36:39], v[148:151]
	v_mfma_f32_16x16x32_bf16 v[144:147], v[120:123], v[84:87], v[144:147]
	ds_read_b128 v[230:233], v204 offset:33600
	s_waitcnt lgkmcnt(4)
	v_mfma_f32_16x16x32_bf16 v[140:143], v[124:127], v[36:39], v[140:143]
	v_mfma_f32_16x16x32_bf16 v[136:139], v[124:127], v[84:87], v[136:139]
	s_waitcnt lgkmcnt(3)
	v_mfma_f32_16x16x32_bf16 v[148:151], v[128:131], v[40:43], v[148:151]
	v_mfma_f32_16x16x32_bf16 v[144:147], v[128:131], v[88:91], v[144:147]
	s_waitcnt lgkmcnt(2)
	v_mfma_f32_16x16x32_bf16 v[140:143], v[132:135], v[40:43], v[140:143]
	v_mfma_f32_16x16x32_bf16 v[136:139], v[132:135], v[88:91], v[136:139]
	s_waitcnt lgkmcnt(1)
	v_mfma_f32_16x16x32_bf16 v[148:151], v[226:229], v[44:47], v[148:151]
	v_mfma_f32_16x16x32_bf16 v[144:147], v[226:229], v[92:95], v[144:147]
	s_waitcnt lgkmcnt(0)
	v_mfma_f32_16x16x32_bf16 v[140:143], v[230:233], v[44:47], v[140:143]
	v_mfma_f32_16x16x32_bf16 v[136:139], v[230:233], v[92:95], v[136:139]
	s_nop 1
	ds_read2st64_b32 v[170:171], v185 offset1:3
	ds_read_b32 v205, v185 offset:1536
	ds_read_u16 v226, v197 offset:26880
	ds_read_u16 v227, v197 offset:27280
	ds_read_u16 v228, v197 offset:27680
	ds_read_u16 v229, v197 offset:28080
	ds_read_u16 v230, v197 offset:33280
	ds_read_u16 v231, v197 offset:33680
	ds_read_u16 v232, v197 offset:34080
	ds_read_u16 v233, v197 offset:34480
	s_waitcnt lgkmcnt(8)
; #define LAS __attribute__((address_space(3)))
; DI unsigned pk2(float a, float b) { f32x2 v = {a, b}; bf2_t r = __builtin_convertvector(v, bf2_t); return __builtin_bit_cast(unsigned, r); }
; DI void phase_rglru(const Params& p, unsigned char* shm) {
;     ...
;                     const float ba = gb[ch], bx = gb[192 + ch], sp = gb[384 + ch];
; #pragma unroll
;                     for (int mt = 0; mt < 4; ++mt)
; #pragma unroll
;                         for (int j = 0; j < 4; ++j) {
;                             const int t = 16 * mt + 4 * fq + j;
;                             const float ea = 1.f + __expf(fminf(-(acc[mt][0][j] + ba), 40.f)), ex = 1.f + __expf(fminf(-(acc[mt][1][j] + bx), 40.f));
;                             const float inv = __builtin_amdgcn_rcpf(ea * ex);
;                             const float r = inv * ex, ig = inv * ea;
;                             const float av = __expf(r * sp), om = 1.f - av;
;                             const float xcv = __uint_as_float((unsigned)*(const LAS bf16_t*)(lds + XC + t * TR + ch * 2) << 16);
;                             const float bt = __builtin_amdgcn_sqrtf(fmaxf(om * (1.f + av), 0.f)) * (ig * xcv);
;                             *(LAS bf16_t*)(lds + LAo + t * TR + ch * 2) = (bf16_t)(pk2(om, 0.f) & 0xffffu);
;                             *(LAS bf16_t*)(lds + BTo + t * TR + ch * 2) = (bf16_t)(pk2(bt, 0.f) & 0xffffu);
;                         }
	v_mov_b32_e32 v242, 0xbfb8aa3b
	v_mov_b32_e32 v243, 0x4266d4ca
	v_mul_f32_e32 v170, v242, v170
	v_mul_f32_e32 v171, v242, v171
	v_mul_f32_e32 v205, 0x3fb8aa3b, v205
	v_pk_fma_f32 v[148:149], v[148:149], v[242:243], v[170:171] op_sel_hi:[1,0,0]
	v_pk_fma_f32 v[144:145], v[144:145], v[242:243], v[170:171] op_sel:[0,0,1] op_sel_hi:[1,0,1]
	v_pk_fma_f32 v[150:151], v[150:151], v[242:243], v[170:171] op_sel_hi:[1,0,0]
	v_pk_fma_f32 v[146:147], v[146:147], v[242:243], v[170:171] op_sel:[0,0,1] op_sel_hi:[1,0,1]
	v_pk_fma_f32 v[140:141], v[140:141], v[242:243], v[170:171] op_sel_hi:[1,0,0]
	v_pk_fma_f32 v[136:137], v[136:137], v[242:243], v[170:171] op_sel:[0,0,1] op_sel_hi:[1,0,1]
	v_pk_fma_f32 v[142:143], v[142:143], v[242:243], v[170:171] op_sel_hi:[1,0,0]
	v_pk_fma_f32 v[138:139], v[138:139], v[242:243], v[170:171] op_sel:[0,0,1] op_sel_hi:[1,0,1]
	v_min_f32_e32 v148, v243, v148
	v_min_f32_e32 v149, v243, v149
	v_min_f32_e32 v144, v243, v144
	v_min_f32_e32 v145, v243, v145
	v_min_f32_e32 v150, v243, v150
	v_min_f32_e32 v151, v243, v151
	v_min_f32_e32 v146, v243, v146
	v_min_f32_e32 v147, v243, v147
	v_min_f32_e32 v140, v243, v140
	v_min_f32_e32 v141, v243, v141
	v_min_f32_e32 v136, v243, v136
	v_min_f32_e32 v137, v243, v137
	v_min_f32_e32 v142, v243, v142
	v_min_f32_e32 v143, v243, v143
	v_min_f32_e32 v138, v243, v138
	v_min_f32_e32 v139, v243, v139
	v_exp_f32_e32 v148, v148
	v_exp_f32_e32 v149, v149
	v_exp_f32_e32 v144, v144
	v_exp_f32_e32 v145, v145
	v_exp_f32_e32 v150, v150
	v_exp_f32_e32 v151, v151
	v_exp_f32_e32 v146, v146
	v_exp_f32_e32 v147, v147
	v_exp_f32_e32 v140, v140
	v_exp_f32_e32 v141, v141
	v_exp_f32_e32 v136, v136
	v_exp_f32_e32 v137, v137
	v_exp_f32_e32 v142, v142
	v_exp_f32_e32 v143, v143
	v_exp_f32_e32 v138, v138
	v_exp_f32_e32 v139, v139
	v_pk_add_f32 v[148:149], v[148:149], 1.0 op_sel_hi:[1,0]
	v_pk_add_f32 v[144:145], v[144:145], 1.0 op_sel_hi:[1,0]
	v_pk_add_f32 v[150:151], v[150:151], 1.0 op_sel_hi:[1,0]
	v_pk_add_f32 v[146:147], v[146:147], 1.0 op_sel_hi:[1,0]
	v_pk_add_f32 v[140:141], v[140:141], 1.0 op_sel_hi:[1,0]
	v_pk_add_f32 v[136:137], v[136:137], 1.0 op_sel_hi:[1,0]
	v_pk_add_f32 v[142:143], v[142:143], 1.0 op_sel_hi:[1,0]
	v_pk_add_f32 v[138:139], v[138:139], 1.0 op_sel_hi:[1,0]
	v_pk_mul_f32 v[210:211], v[148:149], v[144:145]
	v_pk_mul_f32 v[212:213], v[150:151], v[146:147]
	v_pk_mul_f32 v[214:215], v[140:141], v[136:137]
	v_pk_mul_f32 v[216:217], v[142:143], v[138:139]
	v_rcp_f32_e32 v210, v210
	v_rcp_f32_e32 v211, v211
	v_rcp_f32_e32 v212, v212
	v_rcp_f32_e32 v213, v213
	v_rcp_f32_e32 v214, v214
	v_rcp_f32_e32 v215, v215
	v_rcp_f32_e32 v216, v216
	v_rcp_f32_e32 v217, v217
	v_pk_mul_f32 v[144:145], v[144:145], v[210:211]
	v_pk_mul_f32 v[148:149], v[148:149], v[210:211]
	v_pk_mul_f32 v[146:147], v[146:147], v[212:213]
	v_pk_mul_f32 v[150:151], v[150:151], v[212:213]
	v_pk_mul_f32 v[136:137], v[136:137], v[214:215]
	v_pk_mul_f32 v[140:141], v[140:141], v[214:215]
	v_pk_mul_f32 v[138:139], v[138:139], v[216:217]
	v_pk_mul_f32 v[142:143], v[142:143], v[216:217]
	v_pk_mul_f32 v[144:145], v[144:145], v[204:205] op_sel:[0,1] op_sel_hi:[1,1]
	v_pk_mul_f32 v[146:147], v[146:147], v[204:205] op_sel:[0,1] op_sel_hi:[1,1]
	v_pk_mul_f32 v[136:137], v[136:137], v[204:205] op_sel:[0,1] op_sel_hi:[1,1]
	v_pk_mul_f32 v[138:139], v[138:139], v[204:205] op_sel:[0,1] op_sel_hi:[1,1]
	v_exp_f32_e32 v144, v144
	v_exp_f32_e32 v145, v145
	v_exp_f32_e32 v146, v146
	v_exp_f32_e32 v147, v147
	v_exp_f32_e32 v136, v136
	v_exp_f32_e32 v137, v137
	v_exp_f32_e32 v138, v138
	v_exp_f32_e32 v139, v139
	v_pk_add_f32 v[210:211], v[144:145], 1.0 op_sel_hi:[1,0] neg_lo:[1,0] neg_hi:[1,0]
	v_pk_add_f32 v[144:145], v[144:145], 1.0 op_sel_hi:[1,0]
	v_pk_add_f32 v[212:213], v[146:147], 1.0 op_sel_hi:[1,0] neg_lo:[1,0] neg_hi:[1,0]
	v_pk_add_f32 v[146:147], v[146:147], 1.0 op_sel_hi:[1,0]
	v_pk_add_f32 v[214:215], v[136:137], 1.0 op_sel_hi:[1,0] neg_lo:[1,0] neg_hi:[1,0]
	v_pk_add_f32 v[136:137], v[136:137], 1.0 op_sel_hi:[1,0]
	v_pk_add_f32 v[216:217], v[138:139], 1.0 op_sel_hi:[1,0] neg_lo:[1,0] neg_hi:[1,0]
	v_pk_add_f32 v[138:139], v[138:139], 1.0 op_sel_hi:[1,0]
	v_pk_mul_f32 v[144:145], v[210:211], v[144:145]
	v_pk_mul_f32 v[146:147], v[212:213], v[146:147]
	v_pk_mul_f32 v[136:137], v[214:215], v[136:137]
	v_pk_mul_f32 v[138:139], v[216:217], v[138:139]
	v_max_f32_e32 v144, 0, v144
	v_max_f32_e32 v145, 0, v145
	v_max_f32_e32 v146, 0, v146
	v_max_f32_e32 v147, 0, v147
	v_max_f32_e32 v136, 0, v136
	v_max_f32_e32 v137, 0, v137
	v_max_f32_e32 v138, 0, v138
	v_max_f32_e32 v139, 0, v139
	v_sqrt_f32_e32 v144, v144
	v_sqrt_f32_e32 v145, v145
	v_sqrt_f32_e32 v146, v146
	v_sqrt_f32_e32 v147, v147
	v_sqrt_f32_e32 v136, v136
	v_sqrt_f32_e32 v137, v137
	v_sqrt_f32_e32 v138, v138
	v_sqrt_f32_e32 v139, v139
	s_waitcnt lgkmcnt(0)
	v_lshlrev_b32_e32 v226, 16, v226
	v_lshlrev_b32_e32 v227, 16, v227
	v_lshlrev_b32_e32 v228, 16, v228
	v_lshlrev_b32_e32 v229, 16, v229
	v_lshlrev_b32_e32 v230, 16, v230
	v_lshlrev_b32_e32 v231, 16, v231
	v_lshlrev_b32_e32 v232, 16, v232
	v_lshlrev_b32_e32 v233, 16, v233
	v_pk_mul_f32 v[148:149], v[148:149], v[226:227]
	v_pk_mul_f32 v[150:151], v[150:151], v[228:229]
	v_pk_mul_f32 v[140:141], v[140:141], v[230:231]
	v_pk_mul_f32 v[142:143], v[142:143], v[232:233]
	v_pk_mul_f32 v[148:149], v[148:149], v[144:145]
	v_pk_mul_f32 v[150:151], v[150:151], v[146:147]
	v_pk_mul_f32 v[140:141], v[140:141], v[136:137]
	v_pk_mul_f32 v[142:143], v[142:143], v[138:139]
	v_cvt_pk_bf16_f32 v210, v210, v211
	v_cvt_pk_bf16_f32 v148, v148, v149
	v_cvt_pk_bf16_f32 v212, v212, v213
	v_cvt_pk_bf16_f32 v150, v150, v151
	v_cvt_pk_bf16_f32 v214, v214, v215
	v_cvt_pk_bf16_f32 v140, v140, v141
	v_cvt_pk_bf16_f32 v216, v216, v217
	v_cvt_pk_bf16_f32 v142, v142, v143
	ds_write_b16 v198, v210
	ds_write_b16_d16_hi v198, v210 offset:400
	ds_write_b16 v199, v148
	ds_write_b16_d16_hi v199, v148 offset:400
	ds_write_b16 v198, v212 offset:800
	ds_write_b16_d16_hi v198, v212 offset:1200
	ds_write_b16 v199, v150 offset:800
	ds_write_b16_d16_hi v199, v150 offset:1200
	ds_write_b16 v198, v214 offset:6400
	ds_write_b16_d16_hi v198, v214 offset:6800
	ds_write_b16 v199, v140 offset:6400
	ds_write_b16_d16_hi v199, v140 offset:6800
	ds_write_b16 v198, v216 offset:7200
	ds_write_b16_d16_hi v198, v216 offset:7600
	ds_write_b16 v199, v142 offset:7200
	ds_write_b16_d16_hi v199, v142 offset:7600
	s_branch .LBB0_847
; #define LAS __attribute__((address_space(3)))
; DI void phase_rglru(const Params& p, unsigned char* shm) {
;     ...
;                     for (int kk = 0; kk < 6; ++kk)
; #pragma unroll
;                         for (int mt = 0; mt < 4; ++mt) {
;                             const bf16x8 af = *(const LAS bf16x8*)(lds + XC + (16 * mt + fr) * TR + (32 * kk + 8 * fq) * 2);
;                             acc[mt][0] = __builtin_amdgcn_mfma_f32_16x16x32_bf16(af, Bf[u][kk], acc[mt][0], 0, 0, 0);
;                             acc[mt][1] = __builtin_amdgcn_mfma_f32_16x16x32_bf16(af, Bf[2 + u][kk], acc[mt][1], 0, 0, 0);
;                         }
;                     const int ch = chb + 16 * u + fr;
;                     const float ba = gb[ch], bx = gb[192 + ch], sp = gb[384 + ch];
; #pragma unroll
;                     for (int mt = 0; mt < 4; ++mt)
; #pragma unroll
;                         for (int j = 0; j < 4; ++j) {
;                             const int t = 16 * mt + 4 * fq + j;
;                             const float ea = 1.f + __expf(fminf(-(acc[mt][0][j] + ba), 40.f)), ex = 1.f + __expf(fminf(-(acc[mt][1][j] + bx), 40.f));
;                             const float inv = __builtin_amdgcn_rcpf(ea * ex);
;                             const float r = inv * ex, ig = inv * ea;
.Lgates_b:
	ds_read_b128 v[120:123], v204 offset:39680
	ds_read_b128 v[124:127], v204 offset:46080
	ds_read_b128 v[128:131], v204 offset:39744
	ds_read_b128 v[132:135], v204 offset:46144
	ds_read_b128 v[226:229], v204 offset:39808
	s_waitcnt lgkmcnt(4)
	v_mfma_f32_16x16x32_bf16 v[214:217], v[120:123], v[24:27], 0
	v_mfma_f32_16x16x32_bf16 v[210:213], v[120:123], v[72:75], 0
	ds_read_b128 v[230:233], v204 offset:46208
	s_waitcnt lgkmcnt(4)
	v_mfma_f32_16x16x32_bf16 v[218:221], v[124:127], v[24:27], 0
	v_mfma_f32_16x16x32_bf16 v[222:225], v[124:127], v[72:75], 0
	ds_read_b128 v[120:123], v204 offset:39872
	s_waitcnt lgkmcnt(4)
	v_mfma_f32_16x16x32_bf16 v[214:217], v[128:131], v[28:31], v[214:217]
	v_mfma_f32_16x16x32_bf16 v[210:213], v[128:131], v[76:79], v[210:213]
	ds_read_b128 v[124:127], v204 offset:46272
	s_waitcnt lgkmcnt(4)
	v_mfma_f32_16x16x32_bf16 v[218:221], v[132:135], v[28:31], v[218:221]
	v_mfma_f32_16x16x32_bf16 v[222:225], v[132:135], v[76:79], v[222:225]
	ds_read_b128 v[128:131], v204 offset:39936
	s_waitcnt lgkmcnt(4)
	v_mfma_f32_16x16x32_bf16 v[214:217], v[226:229], v[32:35], v[214:217]
	v_mfma_f32_16x16x32_bf16 v[210:213], v[226:229], v[80:83], v[210:213]
	ds_read_b128 v[132:135], v204 offset:46336
	s_waitcnt lgkmcnt(4)
	v_mfma_f32_16x16x32_bf16 v[218:221], v[230:233], v[32:35], v[218:221]
	v_mfma_f32_16x16x32_bf16 v[222:225], v[230:233], v[80:83], v[222:225]
	s_waitcnt lgkmcnt(3)
	v_mfma_f32_16x16x32_bf16 v[214:217], v[120:123], v[36:39], v[214:217]
	v_mfma_f32_16x16x32_bf16 v[210:213], v[120:123], v[84:87], v[210:213]
	s_waitcnt lgkmcnt(2)
	v_mfma_f32_16x16x32_bf16 v[218:221], v[124:127], v[36:39], v[218:221]
	v_mfma_f32_16x16x32_bf16 v[222:225], v[124:127], v[84:87], v[222:225]
	s_waitcnt lgkmcnt(1)
	v_mfma_f32_16x16x32_bf16 v[214:217], v[128:131], v[40:43], v[214:217]
	v_mfma_f32_16x16x32_bf16 v[210:213], v[128:131], v[88:91], v[210:213]
	s_waitcnt lgkmcnt(0)
	v_mfma_f32_16x16x32_bf16 v[218:221], v[132:135], v[40:43], v[218:221]
	v_mfma_f32_16x16x32_bf16 v[222:225], v[132:135], v[88:91], v[222:225]
	ds_read_b128 v[120:123], v204 offset:40000
	s_nop 1
	ds_read_b128 v[128:131], v204 offset:46400
	ds_read2st64_b32 v[170:171], v185 offset1:3
	ds_read_b32 v205, v185 offset:1536
	ds_read_u16 v234, v197 offset:39680
	ds_read_u16 v235, v197 offset:40080
	ds_read_u16 v236, v197 offset:40480
	ds_read_u16 v237, v197 offset:40880
	ds_read_u16 v238, v197 offset:46080
	ds_read_u16 v239, v197 offset:46480
	ds_read_u16 v240, v197 offset:46880
	ds_read_u16 v241, v197 offset:47280
	s_waitcnt lgkmcnt(8)
	v_mov_b32_e32 v242, 0xbfb8aa3b
	v_mov_b32_e32 v243, 0x4266d4ca
	v_mul_f32_e32 v170, v242, v170
	v_mul_f32_e32 v171, v242, v171
	v_mul_f32_e32 v205, 0x3fb8aa3b, v205
	v_mfma_f32_16x16x32_bf16 v[124:127], v[120:123], v[44:47], v[214:217]
	v_mfma_f32_16x16x32_bf16 v[120:123], v[120:123], v[92:95], v[210:213]
	v_mfma_f32_16x16x32_bf16 v[132:135], v[128:131], v[44:47], v[218:221]
	v_mfma_f32_16x16x32_bf16 v[128:131], v[128:131], v[92:95], v[222:225]
	s_nop 8
	v_pk_fma_f32 v[124:125], v[124:125], v[242:243], v[170:171] op_sel_hi:[1,0,0]
	v_pk_fma_f32 v[120:121], v[120:121], v[242:243], v[170:171] op_sel:[0,0,1] op_sel_hi:[1,0,1]
	v_pk_fma_f32 v[126:127], v[126:127], v[242:243], v[170:171] op_sel_hi:[1,0,0]
	v_pk_fma_f32 v[122:123], v[122:123], v[242:243], v[170:171] op_sel:[0,0,1] op_sel_hi:[1,0,1]
	v_pk_fma_f32 v[132:133], v[132:133], v[242:243], v[170:171] op_sel_hi:[1,0,0]
	v_pk_fma_f32 v[128:129], v[128:129], v[242:243], v[170:171] op_sel:[0,0,1] op_sel_hi:[1,0,1]
	v_pk_fma_f32 v[134:135], v[134:135], v[242:243], v[170:171] op_sel_hi:[1,0,0]
	v_pk_fma_f32 v[130:131], v[130:131], v[242:243], v[170:171] op_sel:[0,0,1] op_sel_hi:[1,0,1]
	v_min_f32_e32 v124, v243, v124
	v_min_f32_e32 v125, v243, v125
	v_min_f32_e32 v120, v243, v120
	v_min_f32_e32 v121, v243, v121
	v_min_f32_e32 v126, v243, v126
	v_min_f32_e32 v127, v243, v127
	v_min_f32_e32 v122, v243, v122
	v_min_f32_e32 v123, v243, v123
	v_min_f32_e32 v132, v243, v132
	v_min_f32_e32 v133, v243, v133
	v_min_f32_e32 v128, v243, v128
	v_min_f32_e32 v129, v243, v129
	v_min_f32_e32 v134, v243, v134
	v_min_f32_e32 v135, v243, v135
	v_min_f32_e32 v130, v243, v130
	v_min_f32_e32 v131, v243, v131
	v_exp_f32_e32 v124, v124
	v_exp_f32_e32 v125, v125
	v_exp_f32_e32 v120, v120
	v_exp_f32_e32 v121, v121
	v_exp_f32_e32 v126, v126
	v_exp_f32_e32 v127, v127
	v_exp_f32_e32 v122, v122
	v_exp_f32_e32 v123, v123
	v_exp_f32_e32 v132, v132
	v_exp_f32_e32 v133, v133
	v_exp_f32_e32 v128, v128
	v_exp_f32_e32 v129, v129
	v_exp_f32_e32 v134, v134
	v_exp_f32_e32 v135, v135
	v_exp_f32_e32 v130, v130
	v_exp_f32_e32 v131, v131
	v_pk_add_f32 v[124:125], v[124:125], 1.0 op_sel_hi:[1,0]
	v_pk_add_f32 v[120:121], v[120:121], 1.0 op_sel_hi:[1,0]
	v_pk_add_f32 v[126:127], v[126:127], 1.0 op_sel_hi:[1,0]
	v_pk_add_f32 v[122:123], v[122:123], 1.0 op_sel_hi:[1,0]
	v_pk_add_f32 v[132:133], v[132:133], 1.0 op_sel_hi:[1,0]
	v_pk_add_f32 v[128:129], v[128:129], 1.0 op_sel_hi:[1,0]
	v_pk_add_f32 v[134:135], v[134:135], 1.0 op_sel_hi:[1,0]
	v_pk_add_f32 v[130:131], v[130:131], 1.0 op_sel_hi:[1,0]
	v_pk_mul_f32 v[210:211], v[124:125], v[120:121]
	v_pk_mul_f32 v[212:213], v[126:127], v[122:123]
	v_pk_mul_f32 v[214:215], v[132:133], v[128:129]
	v_pk_mul_f32 v[216:217], v[134:135], v[130:131]
	v_rcp_f32_e32 v210, v210
	v_rcp_f32_e32 v211, v211
	v_rcp_f32_e32 v212, v212
	v_rcp_f32_e32 v213, v213
	v_rcp_f32_e32 v214, v214
	v_rcp_f32_e32 v215, v215
	v_rcp_f32_e32 v216, v216
	v_rcp_f32_e32 v217, v217
	v_pk_mul_f32 v[120:121], v[120:121], v[210:211]
	v_pk_mul_f32 v[124:125], v[124:125], v[210:211]
	v_pk_mul_f32 v[122:123], v[122:123], v[212:213]
; #define LAS __attribute__((address_space(3)))
; DI unsigned pk2(float a, float b) { f32x2 v = {a, b}; bf2_t r = __builtin_convertvector(v, bf2_t); return __builtin_bit_cast(unsigned, r); }
; DI void phase_rglru(const Params& p, unsigned char* shm) {
;     ...
;                     for (int kk = 0; kk < 6; ++kk)
; #pragma unroll
;                         for (int mt = 0; mt < 4; ++mt) {
;                             const bf16x8 af = *(const LAS bf16x8*)(lds + XC + (16 * mt + fr) * TR + (32 * kk + 8 * fq) * 2);
;                             acc[mt][0] = __builtin_amdgcn_mfma_f32_16x16x32_bf16(af, Bf[u][kk], acc[mt][0], 0, 0, 0);
;     ...
;                             const float av = __expf(r * sp), om = 1.f - av;
;                             const float xcv = __uint_as_float((unsigned)*(const LAS bf16_t*)(lds + XC + t * TR + ch * 2) << 16);
;                             const float bt = __builtin_amdgcn_sqrtf(fmaxf(om * (1.f + av), 0.f)) * (ig * xcv);
;                             *(LAS bf16_t*)(lds + LAo + t * TR + ch * 2) = (bf16_t)(pk2(om, 0.f) & 0xffffu);
;                             *(LAS bf16_t*)(lds + BTo + t * TR + ch * 2) = (bf16_t)(pk2(bt, 0.f) & 0xffffu);
;                         }
	v_pk_mul_f32 v[126:127], v[126:127], v[212:213]
	v_pk_mul_f32 v[128:129], v[128:129], v[214:215]
	v_pk_mul_f32 v[132:133], v[132:133], v[214:215]
	v_pk_mul_f32 v[130:131], v[130:131], v[216:217]
	v_pk_mul_f32 v[134:135], v[134:135], v[216:217]
	v_pk_mul_f32 v[120:121], v[120:121], v[204:205] op_sel:[0,1] op_sel_hi:[1,1]
	v_pk_mul_f32 v[122:123], v[122:123], v[204:205] op_sel:[0,1] op_sel_hi:[1,1]
	v_pk_mul_f32 v[128:129], v[128:129], v[204:205] op_sel:[0,1] op_sel_hi:[1,1]
	v_pk_mul_f32 v[130:131], v[130:131], v[204:205] op_sel:[0,1] op_sel_hi:[1,1]
	v_exp_f32_e32 v120, v120
	v_exp_f32_e32 v121, v121
	v_exp_f32_e32 v122, v122
	v_exp_f32_e32 v123, v123
	v_exp_f32_e32 v128, v128
	v_exp_f32_e32 v129, v129
	v_exp_f32_e32 v130, v130
	v_exp_f32_e32 v131, v131
	v_pk_add_f32 v[210:211], v[120:121], 1.0 op_sel_hi:[1,0] neg_lo:[1,0] neg_hi:[1,0]
	v_pk_add_f32 v[120:121], v[120:121], 1.0 op_sel_hi:[1,0]
	v_pk_add_f32 v[212:213], v[122:123], 1.0 op_sel_hi:[1,0] neg_lo:[1,0] neg_hi:[1,0]
	v_pk_add_f32 v[122:123], v[122:123], 1.0 op_sel_hi:[1,0]
	v_pk_add_f32 v[214:215], v[128:129], 1.0 op_sel_hi:[1,0] neg_lo:[1,0] neg_hi:[1,0]
	v_pk_add_f32 v[128:129], v[128:129], 1.0 op_sel_hi:[1,0]
	v_pk_add_f32 v[216:217], v[130:131], 1.0 op_sel_hi:[1,0] neg_lo:[1,0] neg_hi:[1,0]
	v_pk_add_f32 v[130:131], v[130:131], 1.0 op_sel_hi:[1,0]
	v_pk_mul_f32 v[120:121], v[210:211], v[120:121]
	v_pk_mul_f32 v[122:123], v[212:213], v[122:123]
	v_pk_mul_f32 v[128:129], v[214:215], v[128:129]
	v_pk_mul_f32 v[130:131], v[216:217], v[130:131]
	v_max_f32_e32 v120, 0, v120
	v_max_f32_e32 v121, 0, v121
	v_max_f32_e32 v122, 0, v122
	v_max_f32_e32 v123, 0, v123
	v_max_f32_e32 v128, 0, v128
	v_max_f32_e32 v129, 0, v129
	v_max_f32_e32 v130, 0, v130
	v_max_f32_e32 v131, 0, v131
	v_sqrt_f32_e32 v120, v120
	v_sqrt_f32_e32 v121, v121
	v_sqrt_f32_e32 v122, v122
	v_sqrt_f32_e32 v123, v123
	v_sqrt_f32_e32 v128, v128
	v_sqrt_f32_e32 v129, v129
	v_sqrt_f32_e32 v130, v130
	v_sqrt_f32_e32 v131, v131
	s_waitcnt lgkmcnt(0)
	v_lshlrev_b32_e32 v234, 16, v234
	v_lshlrev_b32_e32 v235, 16, v235
	v_lshlrev_b32_e32 v236, 16, v236
	v_lshlrev_b32_e32 v237, 16, v237
	v_lshlrev_b32_e32 v238, 16, v238
	v_lshlrev_b32_e32 v239, 16, v239
	v_lshlrev_b32_e32 v240, 16, v240
	v_lshlrev_b32_e32 v241, 16, v241
	v_pk_mul_f32 v[124:125], v[124:125], v[234:235]
	v_pk_mul_f32 v[126:127], v[126:127], v[236:237]
	v_pk_mul_f32 v[132:133], v[132:133], v[238:239]
	v_pk_mul_f32 v[134:135], v[134:135], v[240:241]
	v_pk_mul_f32 v[124:125], v[124:125], v[120:121]
	v_pk_mul_f32 v[126:127], v[126:127], v[122:123]
	v_pk_mul_f32 v[132:133], v[132:133], v[128:129]
	v_pk_mul_f32 v[134:135], v[134:135], v[130:131]
	v_cvt_pk_bf16_f32 v210, v210, v211
	v_cvt_pk_bf16_f32 v124, v124, v125
	v_cvt_pk_bf16_f32 v212, v212, v213
	v_cvt_pk_bf16_f32 v126, v126, v127
	v_cvt_pk_bf16_f32 v214, v214, v215
	v_cvt_pk_bf16_f32 v132, v132, v133
	v_cvt_pk_bf16_f32 v216, v216, v217
	v_cvt_pk_bf16_f32 v134, v134, v135
	ds_write_b16 v198, v210 offset:12800
	ds_write_b16_d16_hi v198, v210 offset:13200
	ds_write_b16 v199, v124 offset:12800
	ds_write_b16_d16_hi v199, v124 offset:13200
	ds_write_b16 v198, v212 offset:13600
	ds_write_b16_d16_hi v198, v212 offset:14000
	ds_write_b16 v199, v126 offset:13600
	ds_write_b16_d16_hi v199, v126 offset:14000
	ds_write_b16 v198, v214 offset:19200
	ds_write_b16_d16_hi v198, v214 offset:19600
	ds_write_b16 v199, v132 offset:19200
	ds_write_b16_d16_hi v199, v132 offset:19600
	ds_write_b16 v198, v216 offset:20000
	ds_write_b16_d16_hi v198, v216 offset:20400
	ds_write_b16 v199, v134 offset:20000
	ds_write_b16_d16_hi v199, v134 offset:20400
	ds_read_b128 v[120:123], v204 offset:26880
	ds_read_b128 v[124:127], v204 offset:33280
	ds_read_b128 v[128:131], v204 offset:39680
	ds_read_b128 v[132:135], v204 offset:46080
	ds_read_b128 v[226:229], v204 offset:26944
	s_waitcnt lgkmcnt(4)
	v_mfma_f32_16x16x32_bf16 v[148:151], v[120:123], v[0:3], 0
	v_mfma_f32_16x16x32_bf16 v[144:147], v[120:123], v[48:51], 0
	ds_read_b128 v[230:233], v204 offset:33344
	s_waitcnt lgkmcnt(4)
	v_mfma_f32_16x16x32_bf16 v[140:143], v[124:127], v[0:3], 0
	v_mfma_f32_16x16x32_bf16 v[136:139], v[124:127], v[48:51], 0
	ds_read_b128 v[120:123], v204 offset:39744
	s_waitcnt lgkmcnt(4)
	v_mfma_f32_16x16x32_bf16 v[214:217], v[128:131], v[0:3], 0
	v_mfma_f32_16x16x32_bf16 v[210:213], v[128:131], v[48:51], 0
	ds_read_b128 v[124:127], v204 offset:46144
	s_waitcnt lgkmcnt(4)
	v_mfma_f32_16x16x32_bf16 v[218:221], v[132:135], v[0:3], 0
	v_mfma_f32_16x16x32_bf16 v[222:225], v[132:135], v[48:51], 0
	ds_read_b128 v[128:131], v204 offset:27008
	s_waitcnt lgkmcnt(4)
	v_mfma_f32_16x16x32_bf16 v[148:151], v[226:229], v[4:7], v[148:151]
	v_mfma_f32_16x16x32_bf16 v[144:147], v[226:229], v[52:55], v[144:147]
	ds_read_b128 v[132:135], v204 offset:33408
	s_waitcnt lgkmcnt(4)
	v_mfma_f32_16x16x32_bf16 v[140:143], v[230:233], v[4:7], v[140:143]
	v_mfma_f32_16x16x32_bf16 v[136:139], v[230:233], v[52:55], v[136:139]
	ds_read_b128 v[226:229], v204 offset:39808
	s_waitcnt lgkmcnt(4)
	v_mfma_f32_16x16x32_bf16 v[214:217], v[120:123], v[4:7], v[214:217]
	v_mfma_f32_16x16x32_bf16 v[210:213], v[120:123], v[52:55], v[210:213]
	ds_read_b128 v[230:233], v204 offset:46208
	s_waitcnt lgkmcnt(4)
	v_mfma_f32_16x16x32_bf16 v[218:221], v[124:127], v[4:7], v[218:221]
	v_mfma_f32_16x16x32_bf16 v[222:225], v[124:127], v[52:55], v[222:225]
	ds_read_b128 v[120:123], v204 offset:27072
	s_waitcnt lgkmcnt(4)
	v_mfma_f32_16x16x32_bf16 v[148:151], v[128:131], v[8:11], v[148:151]
	v_mfma_f32_16x16x32_bf16 v[144:147], v[128:131], v[56:59], v[144:147]
	ds_read_b128 v[124:127], v204 offset:33472
	s_waitcnt lgkmcnt(4)
; #define LAS __attribute__((address_space(3)))
; DI void phase_rglru(const Params& p, unsigned char* shm) {
;     ...
;                     for (int kk = 0; kk < 6; ++kk)
; #pragma unroll
;                         for (int mt = 0; mt < 4; ++mt) {
;                             const bf16x8 af = *(const LAS bf16x8*)(lds + XC + (16 * mt + fr) * TR + (32 * kk + 8 * fq) * 2);
;                             acc[mt][0] = __builtin_amdgcn_mfma_f32_16x16x32_bf16(af, Bf[u][kk], acc[mt][0], 0, 0, 0);
;                             acc[mt][1] = __builtin_amdgcn_mfma_f32_16x16x32_bf16(af, Bf[2 + u][kk], acc[mt][1], 0, 0, 0);
;                         }
;                     const int ch = chb + 16 * u + fr;
;                     const float ba = gb[ch], bx = gb[192 + ch], sp = gb[384 + ch];
; #pragma unroll
;                     for (int mt = 0; mt < 4; ++mt)
; #pragma unroll
;                         for (int j = 0; j < 4; ++j) {
;                             const int t = 16 * mt + 4 * fq + j;
;                             const float ea = 1.f + __expf(fminf(-(acc[mt][0][j] + ba), 40.f)), ex = 1.f + __expf(fminf(-(acc[mt][1][j] + bx), 40.f));
	v_mfma_f32_16x16x32_bf16 v[140:143], v[132:135], v[8:11], v[140:143]
	v_mfma_f32_16x16x32_bf16 v[136:139], v[132:135], v[56:59], v[136:139]
	ds_read_b128 v[128:131], v204 offset:39872
	s_waitcnt lgkmcnt(4)
	v_mfma_f32_16x16x32_bf16 v[214:217], v[226:229], v[8:11], v[214:217]
	v_mfma_f32_16x16x32_bf16 v[210:213], v[226:229], v[56:59], v[210:213]
	ds_read_b128 v[132:135], v204 offset:46272
	s_waitcnt lgkmcnt(4)
	v_mfma_f32_16x16x32_bf16 v[218:221], v[230:233], v[8:11], v[218:221]
	v_mfma_f32_16x16x32_bf16 v[222:225], v[230:233], v[56:59], v[222:225]
	ds_read_b128 v[226:229], v204 offset:27136
	s_waitcnt lgkmcnt(4)
	v_mfma_f32_16x16x32_bf16 v[148:151], v[120:123], v[12:15], v[148:151]
	v_mfma_f32_16x16x32_bf16 v[144:147], v[120:123], v[60:63], v[144:147]
	ds_read_b128 v[230:233], v204 offset:33536
	s_waitcnt lgkmcnt(4)
	v_mfma_f32_16x16x32_bf16 v[140:143], v[124:127], v[12:15], v[140:143]
	v_mfma_f32_16x16x32_bf16 v[136:139], v[124:127], v[60:63], v[136:139]
	ds_read_b128 v[120:123], v204 offset:39936
	s_waitcnt lgkmcnt(4)
	v_mfma_f32_16x16x32_bf16 v[214:217], v[128:131], v[12:15], v[214:217]
	v_mfma_f32_16x16x32_bf16 v[210:213], v[128:131], v[60:63], v[210:213]
	ds_read_b128 v[124:127], v204 offset:46336
	s_waitcnt lgkmcnt(4)
	v_mfma_f32_16x16x32_bf16 v[218:221], v[132:135], v[12:15], v[218:221]
	v_mfma_f32_16x16x32_bf16 v[222:225], v[132:135], v[60:63], v[222:225]
	ds_read_b128 v[128:131], v204 offset:27200
	s_waitcnt lgkmcnt(4)
	v_mfma_f32_16x16x32_bf16 v[148:151], v[226:229], v[16:19], v[148:151]
	v_mfma_f32_16x16x32_bf16 v[144:147], v[226:229], v[64:67], v[144:147]
	ds_read_b128 v[132:135], v204 offset:33600
	s_waitcnt lgkmcnt(4)
	v_mfma_f32_16x16x32_bf16 v[140:143], v[230:233], v[16:19], v[140:143]
	v_mfma_f32_16x16x32_bf16 v[136:139], v[230:233], v[64:67], v[136:139]
	s_waitcnt lgkmcnt(3)
	v_mfma_f32_16x16x32_bf16 v[214:217], v[120:123], v[16:19], v[214:217]
	v_mfma_f32_16x16x32_bf16 v[210:213], v[120:123], v[64:67], v[210:213]
	s_waitcnt lgkmcnt(2)
	v_mfma_f32_16x16x32_bf16 v[218:221], v[124:127], v[16:19], v[218:221]
	v_mfma_f32_16x16x32_bf16 v[222:225], v[124:127], v[64:67], v[222:225]
	s_waitcnt lgkmcnt(1)
	v_mfma_f32_16x16x32_bf16 v[148:151], v[128:131], v[20:23], v[148:151]
	v_mfma_f32_16x16x32_bf16 v[144:147], v[128:131], v[68:71], v[144:147]
	s_waitcnt lgkmcnt(0)
	v_mfma_f32_16x16x32_bf16 v[140:143], v[132:135], v[20:23], v[140:143]
	v_mfma_f32_16x16x32_bf16 v[136:139], v[132:135], v[68:71], v[136:139]
	ds_read_b128 v[120:123], v204 offset:40000
	s_nop 1
	ds_read_b128 v[128:131], v204 offset:46400
	ds_read2st64_b32 v[170:171], v184 offset1:3
	ds_read_b32 v205, v184 offset:1536
	ds_read_u16 v226, v194 offset:26880
	ds_read_u16 v227, v194 offset:27280
	ds_read_u16 v228, v194 offset:27680
	ds_read_u16 v229, v194 offset:28080
	ds_read_u16 v230, v194 offset:33280
	ds_read_u16 v231, v194 offset:33680
	ds_read_u16 v232, v194 offset:34080
	ds_read_u16 v233, v194 offset:34480
	ds_read_u16 v234, v194 offset:39680
	ds_read_u16 v235, v194 offset:40080
	ds_read_u16 v236, v194 offset:40480
	ds_read_u16 v237, v194 offset:40880
	ds_read_u16 v238, v194 offset:46080
	ds_read_u16 v239, v194 offset:46480
	ds_read_u16 v240, v194 offset:46880
	ds_read_u16 v241, v194 offset:47280
	s_waitcnt lgkmcnt(15)
	v_mov_b32_e32 v242, 0xbfb8aa3b
	v_mov_b32_e32 v243, 0x4266d4ca
	v_mul_f32_e32 v170, v242, v170
	v_mul_f32_e32 v171, v242, v171
	v_mul_f32_e32 v205, 0x3fb8aa3b, v205
	v_mfma_f32_16x16x32_bf16 v[124:127], v[120:123], v[20:23], v[214:217]
	v_mfma_f32_16x16x32_bf16 v[120:123], v[120:123], v[68:71], v[210:213]
	v_mfma_f32_16x16x32_bf16 v[132:135], v[128:131], v[20:23], v[218:221]
	v_mfma_f32_16x16x32_bf16 v[128:131], v[128:131], v[68:71], v[222:225]
	v_pk_fma_f32 v[148:149], v[148:149], v[242:243], v[170:171] op_sel_hi:[1,0,0]
	v_pk_fma_f32 v[144:145], v[144:145], v[242:243], v[170:171] op_sel:[0,0,1] op_sel_hi:[1,0,1]
	v_pk_fma_f32 v[150:151], v[150:151], v[242:243], v[170:171] op_sel_hi:[1,0,0]
	v_pk_fma_f32 v[146:147], v[146:147], v[242:243], v[170:171] op_sel:[0,0,1] op_sel_hi:[1,0,1]
	v_pk_fma_f32 v[140:141], v[140:141], v[242:243], v[170:171] op_sel_hi:[1,0,0]
	v_pk_fma_f32 v[136:137], v[136:137], v[242:243], v[170:171] op_sel:[0,0,1] op_sel_hi:[1,0,1]
	v_pk_fma_f32 v[142:143], v[142:143], v[242:243], v[170:171] op_sel_hi:[1,0,0]
	v_pk_fma_f32 v[138:139], v[138:139], v[242:243], v[170:171] op_sel:[0,0,1] op_sel_hi:[1,0,1]
	s_nop 0
	v_pk_fma_f32 v[124:125], v[124:125], v[242:243], v[170:171] op_sel_hi:[1,0,0]
	v_pk_fma_f32 v[120:121], v[120:121], v[242:243], v[170:171] op_sel:[0,0,1] op_sel_hi:[1,0,1]
	v_pk_fma_f32 v[126:127], v[126:127], v[242:243], v[170:171] op_sel_hi:[1,0,0]
	v_pk_fma_f32 v[122:123], v[122:123], v[242:243], v[170:171] op_sel:[0,0,1] op_sel_hi:[1,0,1]
	v_pk_fma_f32 v[132:133], v[132:133], v[242:243], v[170:171] op_sel_hi:[1,0,0]
	v_pk_fma_f32 v[128:129], v[128:129], v[242:243], v[170:171] op_sel:[0,0,1] op_sel_hi:[1,0,1]
	v_pk_fma_f32 v[134:135], v[134:135], v[242:243], v[170:171] op_sel_hi:[1,0,0]
	v_pk_fma_f32 v[130:131], v[130:131], v[242:243], v[170:171] op_sel:[0,0,1] op_sel_hi:[1,0,1]
	v_min_f32_e32 v148, v243, v148
	v_min_f32_e32 v149, v243, v149
	v_min_f32_e32 v144, v243, v144
	v_min_f32_e32 v145, v243, v145
	v_min_f32_e32 v150, v243, v150
	v_min_f32_e32 v151, v243, v151
	v_min_f32_e32 v146, v243, v146
	v_min_f32_e32 v147, v243, v147
	v_min_f32_e32 v140, v243, v140
	v_min_f32_e32 v141, v243, v141
	v_min_f32_e32 v136, v243, v136
	v_min_f32_e32 v137, v243, v137
	v_min_f32_e32 v142, v243, v142
	v_min_f32_e32 v143, v243, v143
	v_min_f32_e32 v138, v243, v138
	v_min_f32_e32 v139, v243, v139
	v_min_f32_e32 v124, v243, v124
; DI void phase_rglru(const Params& p, unsigned char* shm) {
;     ...
;                             const float ea = 1.f + __expf(fminf(-(acc[mt][0][j] + ba), 40.f)), ex = 1.f + __expf(fminf(-(acc[mt][1][j] + bx), 40.f));
;                             const float inv = __builtin_amdgcn_rcpf(ea * ex);
;                             const float r = inv * ex, ig = inv * ea;
;                             const float av = __expf(r * sp), om = 1.f - av;
	v_min_f32_e32 v125, v243, v125
	v_min_f32_e32 v120, v243, v120
	v_min_f32_e32 v121, v243, v121
	v_min_f32_e32 v126, v243, v126
	v_min_f32_e32 v127, v243, v127
	v_min_f32_e32 v122, v243, v122
	v_min_f32_e32 v123, v243, v123
	v_min_f32_e32 v132, v243, v132
	v_min_f32_e32 v133, v243, v133
	v_min_f32_e32 v128, v243, v128
	v_min_f32_e32 v129, v243, v129
	v_min_f32_e32 v134, v243, v134
	v_min_f32_e32 v135, v243, v135
	v_min_f32_e32 v130, v243, v130
	v_min_f32_e32 v131, v243, v131
	v_exp_f32_e32 v148, v148
	v_exp_f32_e32 v149, v149
	v_exp_f32_e32 v144, v144
	v_exp_f32_e32 v145, v145
	v_exp_f32_e32 v150, v150
	v_exp_f32_e32 v151, v151
	v_exp_f32_e32 v146, v146
	v_exp_f32_e32 v147, v147
	v_exp_f32_e32 v140, v140
	v_exp_f32_e32 v141, v141
	v_exp_f32_e32 v136, v136
	v_exp_f32_e32 v137, v137
	v_exp_f32_e32 v142, v142
	v_exp_f32_e32 v143, v143
	v_exp_f32_e32 v138, v138
	v_exp_f32_e32 v139, v139
	v_exp_f32_e32 v124, v124
	v_exp_f32_e32 v125, v125
	v_exp_f32_e32 v120, v120
	v_exp_f32_e32 v121, v121
	v_exp_f32_e32 v126, v126
	v_exp_f32_e32 v127, v127
	v_exp_f32_e32 v122, v122
	v_exp_f32_e32 v123, v123
	v_exp_f32_e32 v132, v132
	v_exp_f32_e32 v133, v133
	v_exp_f32_e32 v128, v128
	v_exp_f32_e32 v129, v129
	v_exp_f32_e32 v134, v134
	v_exp_f32_e32 v135, v135
	v_exp_f32_e32 v130, v130
	v_exp_f32_e32 v131, v131
	v_pk_add_f32 v[148:149], v[148:149], 1.0 op_sel_hi:[1,0]
	v_pk_add_f32 v[144:145], v[144:145], 1.0 op_sel_hi:[1,0]
	v_pk_add_f32 v[150:151], v[150:151], 1.0 op_sel_hi:[1,0]
	v_pk_add_f32 v[146:147], v[146:147], 1.0 op_sel_hi:[1,0]
	v_pk_add_f32 v[140:141], v[140:141], 1.0 op_sel_hi:[1,0]
	v_pk_add_f32 v[136:137], v[136:137], 1.0 op_sel_hi:[1,0]
	v_pk_add_f32 v[142:143], v[142:143], 1.0 op_sel_hi:[1,0]
	v_pk_add_f32 v[138:139], v[138:139], 1.0 op_sel_hi:[1,0]
	v_pk_add_f32 v[124:125], v[124:125], 1.0 op_sel_hi:[1,0]
	v_pk_add_f32 v[120:121], v[120:121], 1.0 op_sel_hi:[1,0]
	v_pk_add_f32 v[126:127], v[126:127], 1.0 op_sel_hi:[1,0]
	v_pk_add_f32 v[122:123], v[122:123], 1.0 op_sel_hi:[1,0]
	v_pk_add_f32 v[132:133], v[132:133], 1.0 op_sel_hi:[1,0]
	v_pk_add_f32 v[128:129], v[128:129], 1.0 op_sel_hi:[1,0]
	v_pk_add_f32 v[134:135], v[134:135], 1.0 op_sel_hi:[1,0]
	v_pk_add_f32 v[130:131], v[130:131], 1.0 op_sel_hi:[1,0]
	v_pk_mul_f32 v[210:211], v[148:149], v[144:145]
	v_pk_mul_f32 v[212:213], v[150:151], v[146:147]
	v_pk_mul_f32 v[214:215], v[140:141], v[136:137]
	v_pk_mul_f32 v[216:217], v[142:143], v[138:139]
	v_pk_mul_f32 v[218:219], v[124:125], v[120:121]
	v_pk_mul_f32 v[220:221], v[126:127], v[122:123]
	v_pk_mul_f32 v[222:223], v[132:133], v[128:129]
	v_pk_mul_f32 v[224:225], v[134:135], v[130:131]
	v_rcp_f32_e32 v210, v210
	v_rcp_f32_e32 v211, v211
	v_rcp_f32_e32 v212, v212
	v_rcp_f32_e32 v213, v213
	v_rcp_f32_e32 v214, v214
	v_rcp_f32_e32 v215, v215
	v_rcp_f32_e32 v216, v216
	v_rcp_f32_e32 v217, v217
	v_rcp_f32_e32 v218, v218
	v_rcp_f32_e32 v219, v219
	v_rcp_f32_e32 v220, v220
	v_rcp_f32_e32 v221, v221
	v_rcp_f32_e32 v222, v222
	v_rcp_f32_e32 v223, v223
	v_rcp_f32_e32 v224, v224
	v_rcp_f32_e32 v225, v225
	v_pk_mul_f32 v[144:145], v[144:145], v[210:211]
	v_pk_mul_f32 v[148:149], v[148:149], v[210:211]
	v_pk_mul_f32 v[146:147], v[146:147], v[212:213]
	v_pk_mul_f32 v[150:151], v[150:151], v[212:213]
	v_pk_mul_f32 v[136:137], v[136:137], v[214:215]
	v_pk_mul_f32 v[140:141], v[140:141], v[214:215]
	v_pk_mul_f32 v[138:139], v[138:139], v[216:217]
	v_pk_mul_f32 v[142:143], v[142:143], v[216:217]
	v_pk_mul_f32 v[120:121], v[120:121], v[218:219]
	v_pk_mul_f32 v[124:125], v[124:125], v[218:219]
	v_pk_mul_f32 v[122:123], v[122:123], v[220:221]
	v_pk_mul_f32 v[126:127], v[126:127], v[220:221]
	v_pk_mul_f32 v[128:129], v[128:129], v[222:223]
	v_pk_mul_f32 v[132:133], v[132:133], v[222:223]
	v_pk_mul_f32 v[130:131], v[130:131], v[224:225]
	v_pk_mul_f32 v[134:135], v[134:135], v[224:225]
	v_pk_mul_f32 v[144:145], v[144:145], v[204:205] op_sel:[0,1] op_sel_hi:[1,1]
	v_pk_mul_f32 v[146:147], v[146:147], v[204:205] op_sel:[0,1] op_sel_hi:[1,1]
	v_pk_mul_f32 v[136:137], v[136:137], v[204:205] op_sel:[0,1] op_sel_hi:[1,1]
	v_pk_mul_f32 v[138:139], v[138:139], v[204:205] op_sel:[0,1] op_sel_hi:[1,1]
	v_pk_mul_f32 v[120:121], v[120:121], v[204:205] op_sel:[0,1] op_sel_hi:[1,1]
	v_pk_mul_f32 v[122:123], v[122:123], v[204:205] op_sel:[0,1] op_sel_hi:[1,1]
	v_pk_mul_f32 v[128:129], v[128:129], v[204:205] op_sel:[0,1] op_sel_hi:[1,1]
	v_pk_mul_f32 v[130:131], v[130:131], v[204:205] op_sel:[0,1] op_sel_hi:[1,1]
	v_exp_f32_e32 v144, v144
	v_exp_f32_e32 v145, v145
	v_exp_f32_e32 v146, v146
	v_exp_f32_e32 v147, v147
	v_exp_f32_e32 v136, v136
	v_exp_f32_e32 v137, v137
	v_exp_f32_e32 v138, v138
	v_exp_f32_e32 v139, v139
	v_exp_f32_e32 v120, v120
	v_exp_f32_e32 v121, v121
	v_exp_f32_e32 v122, v122
	v_exp_f32_e32 v123, v123
	v_exp_f32_e32 v128, v128
	v_exp_f32_e32 v129, v129
	v_exp_f32_e32 v130, v130
	v_exp_f32_e32 v131, v131
	v_pk_add_f32 v[210:211], v[144:145], 1.0 op_sel_hi:[1,0] neg_lo:[1,0] neg_hi:[1,0]
	v_pk_add_f32 v[144:145], v[144:145], 1.0 op_sel_hi:[1,0]
	v_pk_add_f32 v[212:213], v[146:147], 1.0 op_sel_hi:[1,0] neg_lo:[1,0] neg_hi:[1,0]
	v_pk_add_f32 v[146:147], v[146:147], 1.0 op_sel_hi:[1,0]
	v_pk_add_f32 v[214:215], v[136:137], 1.0 op_sel_hi:[1,0] neg_lo:[1,0] neg_hi:[1,0]
; #define LAS __attribute__((address_space(3)))
; DI unsigned pk2(float a, float b) { f32x2 v = {a, b}; bf2_t r = __builtin_convertvector(v, bf2_t); return __builtin_bit_cast(unsigned, r); }
; DI void phase_rglru(const Params& p, unsigned char* shm) {
;     ...
;                             const float av = __expf(r * sp), om = 1.f - av;
;                             const float xcv = __uint_as_float((unsigned)*(const LAS bf16_t*)(lds + XC + t * TR + ch * 2) << 16);
;                             const float bt = __builtin_amdgcn_sqrtf(fmaxf(om * (1.f + av), 0.f)) * (ig * xcv);
;                             *(LAS bf16_t*)(lds + LAo + t * TR + ch * 2) = (bf16_t)(pk2(om, 0.f) & 0xffffu);
;                             *(LAS bf16_t*)(lds + BTo + t * TR + ch * 2) = (bf16_t)(pk2(bt, 0.f) & 0xffffu);
;                         }
	v_pk_add_f32 v[136:137], v[136:137], 1.0 op_sel_hi:[1,0]
	v_pk_add_f32 v[216:217], v[138:139], 1.0 op_sel_hi:[1,0] neg_lo:[1,0] neg_hi:[1,0]
	v_pk_add_f32 v[138:139], v[138:139], 1.0 op_sel_hi:[1,0]
	v_pk_add_f32 v[218:219], v[120:121], 1.0 op_sel_hi:[1,0] neg_lo:[1,0] neg_hi:[1,0]
	v_pk_add_f32 v[120:121], v[120:121], 1.0 op_sel_hi:[1,0]
	v_pk_add_f32 v[220:221], v[122:123], 1.0 op_sel_hi:[1,0] neg_lo:[1,0] neg_hi:[1,0]
	v_pk_add_f32 v[122:123], v[122:123], 1.0 op_sel_hi:[1,0]
	v_pk_add_f32 v[222:223], v[128:129], 1.0 op_sel_hi:[1,0] neg_lo:[1,0] neg_hi:[1,0]
	v_pk_add_f32 v[128:129], v[128:129], 1.0 op_sel_hi:[1,0]
	v_pk_add_f32 v[224:225], v[130:131], 1.0 op_sel_hi:[1,0] neg_lo:[1,0] neg_hi:[1,0]
	v_pk_add_f32 v[130:131], v[130:131], 1.0 op_sel_hi:[1,0]
	v_pk_mul_f32 v[144:145], v[210:211], v[144:145]
	v_pk_mul_f32 v[146:147], v[212:213], v[146:147]
	v_pk_mul_f32 v[136:137], v[214:215], v[136:137]
	v_pk_mul_f32 v[138:139], v[216:217], v[138:139]
	v_pk_mul_f32 v[120:121], v[218:219], v[120:121]
	v_pk_mul_f32 v[122:123], v[220:221], v[122:123]
	v_pk_mul_f32 v[128:129], v[222:223], v[128:129]
	v_pk_mul_f32 v[130:131], v[224:225], v[130:131]
	v_max_f32_e32 v144, 0, v144
	v_max_f32_e32 v145, 0, v145
	v_max_f32_e32 v146, 0, v146
	v_max_f32_e32 v147, 0, v147
	v_max_f32_e32 v136, 0, v136
	v_max_f32_e32 v137, 0, v137
	v_max_f32_e32 v138, 0, v138
	v_max_f32_e32 v139, 0, v139
	v_max_f32_e32 v120, 0, v120
	v_max_f32_e32 v121, 0, v121
	v_max_f32_e32 v122, 0, v122
	v_max_f32_e32 v123, 0, v123
	v_max_f32_e32 v128, 0, v128
	v_max_f32_e32 v129, 0, v129
	v_max_f32_e32 v130, 0, v130
	v_max_f32_e32 v131, 0, v131
	v_sqrt_f32_e32 v144, v144
	v_sqrt_f32_e32 v145, v145
	v_sqrt_f32_e32 v146, v146
	v_sqrt_f32_e32 v147, v147
	v_sqrt_f32_e32 v136, v136
	v_sqrt_f32_e32 v137, v137
	v_sqrt_f32_e32 v138, v138
	v_sqrt_f32_e32 v139, v139
	v_sqrt_f32_e32 v120, v120
	v_sqrt_f32_e32 v121, v121
	v_sqrt_f32_e32 v122, v122
	v_sqrt_f32_e32 v123, v123
	v_sqrt_f32_e32 v128, v128
	v_sqrt_f32_e32 v129, v129
	v_sqrt_f32_e32 v130, v130
	v_sqrt_f32_e32 v131, v131
	s_waitcnt lgkmcnt(0)
	v_lshlrev_b32_e32 v226, 16, v226
	v_lshlrev_b32_e32 v227, 16, v227
	v_lshlrev_b32_e32 v228, 16, v228
	v_lshlrev_b32_e32 v229, 16, v229
	v_lshlrev_b32_e32 v230, 16, v230
	v_lshlrev_b32_e32 v231, 16, v231
	v_lshlrev_b32_e32 v232, 16, v232
	v_lshlrev_b32_e32 v233, 16, v233
	v_lshlrev_b32_e32 v234, 16, v234
	v_lshlrev_b32_e32 v235, 16, v235
	v_lshlrev_b32_e32 v236, 16, v236
	v_lshlrev_b32_e32 v237, 16, v237
	v_lshlrev_b32_e32 v238, 16, v238
	v_lshlrev_b32_e32 v239, 16, v239
	v_lshlrev_b32_e32 v240, 16, v240
	v_lshlrev_b32_e32 v241, 16, v241
	v_pk_mul_f32 v[148:149], v[148:149], v[226:227]
	v_pk_mul_f32 v[150:151], v[150:151], v[228:229]
	v_pk_mul_f32 v[140:141], v[140:141], v[230:231]
	v_pk_mul_f32 v[142:143], v[142:143], v[232:233]
	v_pk_mul_f32 v[124:125], v[124:125], v[234:235]
	v_pk_mul_f32 v[126:127], v[126:127], v[236:237]
	v_pk_mul_f32 v[132:133], v[132:133], v[238:239]
	v_pk_mul_f32 v[134:135], v[134:135], v[240:241]
	v_pk_mul_f32 v[148:149], v[148:149], v[144:145]
	v_pk_mul_f32 v[150:151], v[150:151], v[146:147]
	v_pk_mul_f32 v[140:141], v[140:141], v[136:137]
	v_pk_mul_f32 v[142:143], v[142:143], v[138:139]
	v_pk_mul_f32 v[124:125], v[124:125], v[120:121]
	v_pk_mul_f32 v[126:127], v[126:127], v[122:123]
	v_pk_mul_f32 v[132:133], v[132:133], v[128:129]
	v_pk_mul_f32 v[134:135], v[134:135], v[130:131]
	v_cvt_pk_bf16_f32 v210, v210, v211
	v_cvt_pk_bf16_f32 v148, v148, v149
	v_cvt_pk_bf16_f32 v212, v212, v213
	v_cvt_pk_bf16_f32 v150, v150, v151
	v_cvt_pk_bf16_f32 v214, v214, v215
	v_cvt_pk_bf16_f32 v140, v140, v141
	v_cvt_pk_bf16_f32 v216, v216, v217
	v_cvt_pk_bf16_f32 v142, v142, v143
	v_cvt_pk_bf16_f32 v218, v218, v219
	v_cvt_pk_bf16_f32 v124, v124, v125
	v_cvt_pk_bf16_f32 v220, v220, v221
	v_cvt_pk_bf16_f32 v126, v126, v127
	v_cvt_pk_bf16_f32 v222, v222, v223
	v_cvt_pk_bf16_f32 v132, v132, v133
	v_cvt_pk_bf16_f32 v224, v224, v225
	v_cvt_pk_bf16_f32 v134, v134, v135
	ds_write_b16 v195, v210
	ds_write_b16_d16_hi v195, v210 offset:400
	ds_write_b16 v196, v148
	ds_write_b16_d16_hi v196, v148 offset:400
	ds_write_b16 v195, v212 offset:800
	ds_write_b16_d16_hi v195, v212 offset:1200
	ds_write_b16 v196, v150 offset:800
	ds_write_b16_d16_hi v196, v150 offset:1200
	ds_write_b16 v195, v214 offset:6400
	ds_write_b16_d16_hi v195, v214 offset:6800
	ds_write_b16 v196, v140 offset:6400
	ds_write_b16_d16_hi v196, v140 offset:6800
	ds_write_b16 v195, v216 offset:7200
	ds_write_b16_d16_hi v195, v216 offset:7600
	ds_write_b16 v196, v142 offset:7200
	ds_write_b16_d16_hi v196, v142 offset:7600
	ds_write_b16 v195, v218 offset:12800
	ds_write_b16_d16_hi v195, v218 offset:13200
	ds_write_b16 v196, v124 offset:12800
	ds_write_b16_d16_hi v196, v124 offset:13200
	ds_write_b16 v195, v220 offset:13600
	ds_write_b16_d16_hi v195, v220 offset:14000
	ds_write_b16 v196, v126 offset:13600
	ds_write_b16_d16_hi v196, v126 offset:14000
	ds_write_b16 v195, v222 offset:19200
	ds_write_b16_d16_hi v195, v222 offset:19600
	ds_write_b16 v196, v132 offset:19200
	ds_write_b16_d16_hi v196, v132 offset:19600
	ds_write_b16 v195, v224 offset:20000
	ds_write_b16_d16_hi v195, v224 offset:20400
	ds_write_b16 v196, v134 offset:20000
	ds_write_b16_d16_hi v196, v134 offset:20400
